# layer 1 in fused mode: the grid barrier after the last w_out GEMM is skipped (nothing follows it)
# baseline (speedup 1.0000x reference)
.LBB0_1226:
	s_mov_b64 s[0:1], s[88:89]
	s_getreg_b32 s8, hwreg(HW_REG_XCC_ID, 0, 4)
	s_waitcnt vmcnt(0)
	s_waitcnt lgkmcnt(0)
	s_barrier
	s_mov_b64 s[10:11], exec
	v_readlane_b32 s22, v255, 0
	v_readlane_b32 s23, v254, 1
	s_cmp_eq_u32 s22, 1
	s_cbranch_scc0 .Lfb_go
	s_cmpk_eq_u32 s23, 0x100
	s_cbranch_scc1 .LBB0_1162
.Lfb_go:
	v_readlane_b32 s22, v254, 5
	v_readlane_b32 s23, v254, 6
	s_and_b64 s[22:23], s[10:11], s[22:23]
	s_mov_b64 exec, s[22:23]
	s_cbranch_execz .LBB0_1162
	buffer_inv sc1
	s_load_dwordx2 s[22:23], s[0:1], 0x170
	v_readlane_b32 s24, v254, 45
	v_readlane_b32 s25, v254, 46
	s_and_b32 s8, s8, 15
	v_mov_b32_e32 v0, s24
	v_mov_b32_e32 v1, s25
	ds_read_b32 v2, v0
	ds_read_b32 v3, v1
	s_lshl_b32 s9, s8, 8
	v_mov_b32_e32 v4, 0x1400
	v_mov_b32_e32 v5, 1
	s_waitcnt lgkmcnt(0)
	s_add_u32 s24, s22, s9
	s_addc_u32 s25, s23, 0
	global_atomic_add v6, v4, v5, s[24:25] sc0
	v_cvt_f32_u32_e32 v7, v2
	v_rcp_f32_e32 v7, v7
	s_waitcnt vmcnt(0)
	v_cvt_f32_u32_e32 v8, v6
	v_add_f32_e32 v8, 0.5, v8
	v_mul_f32_e32 v8, v8, v7
	v_cvt_u32_f32_e32 v8, v8
	v_mul_lo_u32 v9, v8, v2
	v_sub_u32_e32 v9, v6, v9
	v_add_u32_e32 v9, 1, v9
	v_cmp_eq_u32_e32 vcc, v9, v2
	v_readfirstlane_b32 s26, v8
	s_cbranch_vccz .Lhb4_follow
	buffer_wbl2 sc1
	s_waitcnt vmcnt(0)
	v_mov_b32_e32 v4, 0x3400
	global_atomic_add v4, v5, s[22:23]
	v_readfirstlane_b32 s27, v3
	s_add_u32 s34, s26, 1
	s_mul_i32 s27, s34, s27
	s_mov_b32 s35, 0
